# split grid barrier + GEMM steps wait at the GEMM join (first next_unit/rotation hidden under the barrier too)
# baseline (speedup 1.0000x reference)
; __device__ __forceinline__ unsigned xb_ld(unsigned* p)              { return __hip_atomic_load(p, __ATOMIC_RELAXED, __HIP_MEMORY_SCOPE_AGENT); }
; #define XB_SPIN(cond, bar) do { unsigned _sp = 0; while (cond) { __builtin_amdgcn_s_sleep(1); \
;     if ((++_sp & 255u) == 0u) { if (xb_ld(&(bar)[XB_TMO])) break; if (_sp > XB_SPIN_CAP) { atomicAdd(&(bar)[XB_TMO], 1u); break; } } } } while (0)
; __device__ __forceinline__ void xcd_barrier(const XcdBarrier& b) {
;     ...
;         XB_SPIN((int)(xb_ld(&bar[XB_TOP]) - target) < 0, bar);
;         asm volatile("s_waitcnt vmcnt(0)" ::: "memory");
;         b.st[2] = target;
;     }
;     __syncthreads();
; __global__ void __launch_bounds__(NTHR, 2) dit_fwd(Args args) {
;     ...
;         if (kind == ST_GEMM) {
;             gm::gemm_phase(lds, C, tid, args);
.LBB0_104:
	s_cmp_eq_u32 s100, 0
	s_cbranch_scc1 .Lp1_skip
	v_readlane_b32 s0, v254, 14
	s_nop 3
	s_cmp_eq_u32 s0, 3
	s_cbranch_scc1 .Lp1_skip
	s_mov_b32 s100, 0
	s_cmp_lg_u32 s95, 0
	s_cbranch_scc1 .Lp1_all
	s_mov_b64 s[0:1], exec
	s_mov_b64 exec, 1
	v_mov_b32_e32 v250, 0x3400
	v_mov_b32_e32 v251, 0
	s_mov_b32 vcc_hi, 0
	v_lshl_add_u64 v[248:249], s[92:93], 0, v[250:251]

; __device__ __forceinline__ unsigned xb_ld(unsigned* p)              { return __hip_atomic_load(p, __ATOMIC_RELAXED, __HIP_MEMORY_SCOPE_AGENT); }
; #define XB_SPIN(cond, bar) do { unsigned _sp = 0; while (cond) { __builtin_amdgcn_s_sleep(1); \
;     if ((++_sp & 255u) == 0u) { if (xb_ld(&(bar)[XB_TMO])) break; if (_sp > XB_SPIN_CAP) { atomicAdd(&(bar)[XB_TMO], 1u); break; } } } } while (0)
; __device__ __forceinline__ void xcd_barrier(const XcdBarrier& b) {
;     ...
;         XB_SPIN((int)(xb_ld(&bar[XB_TOP]) - target) < 0, bar);
;         asm volatile("s_waitcnt vmcnt(0)" ::: "memory");
;         b.st[2] = target;
;     }
;     __syncthreads();
.LBB0_261:
	s_cmp_eq_u32 s100, 0
	s_cbranch_scc1 .Lp2_skip
	s_mov_b32 s100, 0
	v_readlane_b32 vcc_lo, v253, 35
	s_nop 3
	s_cmp_lg_u32 vcc_lo, 0
	s_cbranch_scc1 .Lp2_all
	s_mov_b64 exec, 1
	v_readlane_b32 vcc_lo, v253, 33
	v_readlane_b32 vcc_hi, v253, 34
	v_mov_b32_e32 v250, 0x3400
	v_mov_b32_e32 v251, 0
	s_nop 1
	v_lshl_add_u64 v[248:249], vcc, 0, v[250:251]
	s_mov_b32 vcc_hi, 0

; #define PG8_STAGE(bufoff, gbase, voff) do { _Pragma("unroll") for (int _i = 0; _i < 2; ++_i) { unsigned _vo = (voff)[_i]; asm volatile("" : "+v"(_vo));   \
;         __builtin_amdgcn_global_load_lds((const unsigned*)((const char*)(gbase) + _vo), (LAS unsigned*)(lds + (bufoff) + ldsw + _i * 8192), 16, 0, 0); } } while (0)
; #define PG8_BAR __builtin_amdgcn_s_barrier()
; __device__ __forceinline__ void gemm_phase(LAS unsigned char* lds, const Call& C, const int tid, const Args& args) {
;     const int wid = __builtin_amdgcn_readfirstlane(tid >> 6), lane = tid & 63, wr = wid >> 2, wc = wid & 3, fr = lane & 15, fq = lane >> 4;
;     unsigned voffA[2], voffB[2];
; #pragma unroll
;     for (int i = 0; i < 2; ++i) { int R, Cc; stage_rc(tid * 16 + i * 8192, R, Cc); const int Rb = (R & ~31) + perm32(R & 31);
;         voffA[i] = (unsigned)(R * C.lda + Cc) * 2u; voffB[i] = (unsigned)(Rb * C.ldb + Cc) * 2u; }
;     const size_t kstep = (size_t)(BK * 2);
;     const size_t hstepA = (size_t)HALF * C.lda * 2, hstepB = (size_t)HALF * C.ldb * 2;
;     const unsigned ldsw = (unsigned)wid * 1024u;
;     const int aoff = lds_byte(wr * 64 + fr, fq * 8), boff = lds_byte(wc * 32 + fr, fq * 8);
;     ...
;     Unit cur, nxt; int ui = 0;
;     next_unit(C, 0, cur.pm, cur.pn, cur.kp0, cur.np, cur.slice);
;     if (cur.pm < 0) return;
;     f32x4 acc[2][2][4][2];
; #pragma unroll
;     for (int a = 0; a < 2; ++a)
; #pragma unroll
;         for (int b = 0; b < 2; ++b)
; #pragma unroll
;             for (int m = 0; m < 4; ++m)
; #pragma unroll
;                 for (int n = 0; n < 2; ++n) acc[a][b][m][n] = (f32x4){0.f, 0.f, 0.f, 0.f};
;     bf16x8 At[4][2], B0[2][2], B1[2][2];
;     const char* cA = PG8_APTR(cur); const char* cB = PG8_BPTR(cur);
;     PG8_STAGE(PG8_SB(0, 0), cB, voffB); PG8_STAGE(PG8_SB(0, 1), cB + hstepB, voffB); PG8_STAGE(PG8_SA(0, 0), cA, voffA); PG8_STAGE(PG8_SA(0, 1), cA + hstepA, voffA);
;     if (wr == 1) PG8_BAR;
.Lp2_done:
	s_mov_b64 exec, -1
.Lp2_all:
	s_waitcnt vmcnt(0) lgkmcnt(0)
	s_barrier
.Lp2_skip:
	v_readlane_b32 s24, v254, 19
	v_readlane_b32 s48, v254, 17
	s_cmp_lt_i32 s90, 0
	v_lshlrev_b32_e32 v85, 4, v204
	v_readlane_b32 s4, v254, 11
	v_readlane_b32 s25, v254, 20
	v_readlane_b32 s42, v254, 31
	v_readlane_b32 s44, v254, 39
	v_readlane_b32 s49, v254, 18
	s_cbranch_scc1 .LBB0_502
	v_ashrrev_i32_e32 v1, 31, v85
	v_lshrrev_b32_e32 v1, 22, v1
	v_add_u32_e32 v1, v85, v1
	v_and_b32_e32 v1, 0xfffffc00, v1
	v_sub_u32_e32 v1, v85, v1
	v_ashrrev_i32_e32 v0, 31, v204
	v_lshrrev_b32_e32 v2, 4, v1
	v_lshrrev_b32_e32 v0, 26, v0
	v_bitop3_b32 v2, v2, v1, 32 bitop3:0x6c
	v_ashrrev_i32_e32 v1, 31, v1
	v_add_u32_e32 v0, v204, v0
	v_lshrrev_b32_e32 v1, 26, v1
	v_ashrrev_i32_e32 v0, 6, v0
	v_add_u32_e32 v1, v2, v1
	v_lshlrev_b32_e32 v3, 3, v0
	v_ashrrev_i32_e32 v4, 6, v1
	v_and_b32_e32 v1, 0xc0, v1
	v_and_b32_e32 v3, -16, v3
	v_lshlrev_b32_e32 v0, 5, v0
	v_sub_u32_e32 v1, v2, v1
	v_add_u32_e32 v3, v4, v3
	v_and_b32_e32 v0, 32, v0
	v_ashrrev_i16_sdwa v1, v226, sext(v1) dst_sel:DWORD dst_unused:UNUSED_PAD src0_sel:DWORD src1_sel:BYTE_0
	v_add_u32_sdwa v0, v0, sext(v1) dst_sel:DWORD dst_unused:UNUSED_PAD src0_sel:DWORD src1_sel:WORD_0
	v_lshlrev_b32_e32 v1, 1, v3
	v_lshrrev_b32_e32 v2, 2, v3
	v_and_b32_e32 v4, 3, v4
	s_mov_b32 s4, 0x7fffffe0
	v_and_b32_e32 v1, 24, v1
	v_and_b32_e32 v2, 4, v2
	v_and_or_b32 v4, v3, s4, v4
	v_or3_b32 v1, v4, v2, v1
	v_mul_lo_u32 v2, s52, v3
	v_mul_lo_u32 v1, s52, v1
	v_add_lshl_u32 v205, v2, v0, 1
	v_add_lshl_u32 v242, v1, v0, 1
	v_add_u32_e32 v0, 0x2000, v85
	v_ashrrev_i32_e32 v1, 31, v0
	v_lshrrev_b32_e32 v1, 22, v1
	v_add_u32_e32 v1, v0, v1
	v_ashrrev_i32_e32 v1, 10, v1
	v_mul_i32_i24_e32 v2, 0x400, v1
	v_sub_u32_e32 v0, v0, v2
	v_lshrrev_b32_e32 v2, 4, v0
	v_bitop3_b32 v0, v2, v0, 32 bitop3:0x6c
	v_ashrrev_i32_e32 v3, 31, v0
	v_writelane_b32 v254, s51, 52
	v_lshrrev_b32_e32 v3, 26, v3
	v_writelane_b32 v254, s88, 53
	v_lshlrev_b32_e32 v2, 3, v1
	v_add_u32_e32 v3, v0, v3
	v_writelane_b32 v254, s89, 54
	v_and_b32_e32 v2, -16, v2
	v_ashrrev_i32_e32 v4, 6, v3
	v_writelane_b32 v254, s90, 55
	v_add_u32_e32 v2, v4, v2
	v_and_b32_e32 v4, 3, v4
	v_writelane_b32 v254, s91, 56
	s_ashr_i32 s12, s5, 6
	v_and_or_b32 v4, v2, s4, v4
	s_lshl_b32 s22, s52, 8
	s_mov_b32 s53, s29
	s_lshl_b32 s4, s90, 1
	s_ashr_i32 s13, s5, 8
	s_lshl_b64 s[74:75], s[52:53], 8
	s_lshl_b32 s23, s12, 10
	s_mul_hi_u32 s8, s4, s22
	s_mul_i32 s4, s4, s22
	v_readlane_b32 s34, v254, 25
	v_readlane_b32 s35, v254, 26
	s_add_u32 s4, s34, s4
	s_addc_u32 s14, s35, s8
	s_ashr_i32 s8, s78, 31
	s_lshl_b64 s[76:77], s[52:53], 9
	v_and_b32_e32 v3, 0xc0, v3
	s_mul_i32 s8, s76, s8
	s_mul_hi_u32 s9, s76, s78
	v_lshlrev_b32_e32 v1, 5, v1
	v_sub_u32_e32 v0, v0, v3
	s_add_i32 s8, s9, s8
	s_lshr_b32 s9, s52, 23
	v_and_b32_e32 v1, 32, v1
	v_ashrrev_i16_sdwa v0, v226, sext(v0) dst_sel:DWORD dst_unused:UNUSED_PAD src0_sel:DWORD src1_sel:BYTE_0
	s_mul_i32 s9, s9, s78
	v_add_u32_sdwa v0, v1, sext(v0) dst_sel:DWORD dst_unused:UNUSED_PAD src0_sel:DWORD src1_sel:WORD_0
	v_lshlrev_b32_e32 v1, 1, v2
	v_lshrrev_b32_e32 v3, 2, v2
	s_add_i32 s8, s8, s9
	s_mul_i32 s9, s76, s78
	v_and_b32_e32 v1, 24, v1
	v_and_b32_e32 v3, 4, v3
	s_add_u32 s9, s24, s9
	v_or3_b32 v1, v4, v3, v1
	s_addc_u32 s17, s25, s8
	v_mul_lo_u32 v2, s52, v2
	v_mul_lo_u32 v1, s52, v1
	s_add_u32 s8, s9, s0
	v_add_lshl_u32 v243, v2, v0, 1
	v_add_lshl_u32 v244, v1, v0, 1
	s_addc_u32 s9, s17, s1
	s_add_i32 s20, s23, 0
	v_mov_b32_e32 v0, v242
	s_add_i32 m0, s20, 0x10000
	s_nop 0
	global_load_lds_dwordx4 v0, s[8:9]
	v_mov_b32_e32 v0, v244
	s_add_i32 m0, s20, 0x12000
	s_add_u32 s34, s8, s74
	global_load_lds_dwordx4 v0, s[8:9]
	v_mov_b32_e32 v0, v242
	s_addc_u32 s35, s9, s75
	s_add_i32 m0, s20, 0x14000
	s_nop 0
	global_load_lds_dwordx4 v0, s[34:35]
	v_mov_b32_e32 v0, v244
	s_add_i32 m0, s20, 0x16000
	s_add_u32 s0, s4, s0
	global_load_lds_dwordx4 v0, s[34:35]
	v_mov_b32_e32 v0, v205
	s_addc_u32 s1, s14, s1
	s_mov_b32 m0, s20
	s_add_i32 s72, s20, 0x2000
	global_load_lds_dwordx4 v0, s[0:1]
	v_mov_b32_e32 v0, v243
	s_mov_b32 m0, s72
	s_add_u32 s24, s0, s22
	global_load_lds_dwordx4 v0, s[0:1]
	s_addc_u32 s25, s1, 0
	s_add_i32 s73, s20, 0x4000
	v_mov_b32_e32 v0, v205
	s_mov_b32 m0, s73
	s_add_i32 s4, s20, 0x6000
	global_load_lds_dwordx4 v0, s[24:25]
	v_mov_b32_e32 v0, v243
	s_mov_b32 m0, s4
	s_cmp_eq_u32 s13, 1
	global_load_lds_dwordx4 v0, s[24:25]
	s_cselect_b64 s[24:25], -1, 0
	v_writelane_b32 v254, s24, 57
	s_cmp_lg_u32 s13, 1
	s_nop 0
	v_writelane_b32 v254, s25, 58
	s_cbranch_scc1 .LBB0_264
	s_barrier
